# GEMM unit loops: next-tile coordinates via shifts/masks for the fixed shapes instead of the generic runtime division
# speedup vs baseline: 1.0059x; 1.0059x over previous
.LBB0_608:
	s_add_i32 s68, s68, 1
	s_mul_i32 s16, s68, s74
	s_mul_hi_u32 s17, s68, s3
	s_add_i32 s17, s17, s16
	s_mul_i32 s16, s68, s3
	v_readlane_b32 s18, v252, 0
	s_add_u32 s16, s16, s18
	s_addc_u32 s17, s17, s80
	v_cmp_gt_i64_e32 vcc, s[16:17], v[184:185]
	v_cmp_lt_i64_e64 s[42:43], s[16:17], v[250:251]
	s_cbranch_vccnz .LBB0_610
	s_and_b32 s17, s16, 7
	s_lshr_b32 s18, s16, 3
	s_mulk_i32 s17, 34
	s_add_i32 s17, s17, s18
	s_and_b32 s71, s17, 7
	s_lshr_b32 s18, s17, 4
	s_lshl_b32 s18, s18, 3
	s_add_i32 s71, s71, s18
	s_bfe_u32 s70, s17, 0x10003

.LBB0_757:
	s_add_i32 s51, s51, 1
	s_mul_i32 s16, s51, s74
	s_mul_hi_u32 s17, s51, s3
	s_add_i32 s17, s17, s16
	s_mul_i32 s16, s51, s3
	s_add_u32 s16, s16, s83
	s_addc_u32 s17, s17, s62
	v_cmp_gt_i64_e32 vcc, s[16:17], v[184:185]
	v_cmp_lt_i64_e64 s[40:41], s[16:17], v[250:251]
	s_cbranch_vccnz .LBB0_759
	s_and_b32 s17, s16, 7
	s_lshr_b32 s18, s16, 3
	s_mulk_i32 s17, 34
	s_add_i32 s17, s17, s18
	s_and_b32 s53, s17, 7
	s_lshr_b32 s18, s17, 4
	s_lshl_b32 s18, s18, 3
	s_add_i32 s53, s53, s18
	s_bfe_u32 s52, s17, 0x10003

.LBB0_847:
	s_add_i32 s62, s62, 1
	s_mul_i32 s17, s62, s81
	s_mul_hi_u32 s19, s62, s3
	s_add_i32 s19, s19, s17
	s_mul_i32 s17, s62, s3
	v_readlane_b32 s20, v252, 0
	s_add_u32 s42, s17, s20
	s_addc_u32 s43, s19, s80
	v_mov_b64_e32 v[0:1], s[68:69]
	v_cmp_ge_i64_e32 vcc, s[42:43], v[0:1]
	v_cmp_lt_i64_e64 s[40:41], s[42:43], v[0:1]
	s_cbranch_vccnz .LBB0_849
	s_and_b32 s17, s42, 7
	s_lshr_b32 s19, s42, 3
	s_mul_i32 s17, s17, s27
	s_add_i32 s17, s17, s19
	s_and_b32 s18, s17, 7
	s_lshr_b32 s19, s17, 7
	s_lshl_b32 s19, s19, 3
	s_add_i32 s18, s18, s19
	s_bfe_u32 s16, s17, 0x40003

.LBB0_864:
	s_add_i32 s15, s15, 1
	s_mul_i32 s20, s15, s81
	s_mul_hi_u32 s21, s15, s3
	s_add_i32 s21, s21, s20
	s_mul_i32 s20, s15, s3
	v_readlane_b32 s23, v252, 0
	s_add_u32 s52, s20, s23
	s_addc_u32 s53, s21, s80
	s_waitcnt lgkmcnt(0)
	v_mov_b64_e32 v[0:1], 0x200
	v_cmp_lt_i64_e64 s[42:43], s[52:53], v[0:1]
	v_mov_b64_e32 v[0:1], 0x1ff
	v_cmp_gt_i64_e32 vcc, s[52:53], v[0:1]
	s_cbranch_vccnz .LBB0_870
	s_and_b32 s20, s52, 7
	s_lshr_b32 s21, s52, 3
	s_mulk_i32 s20, 64
	s_add_i32 s20, s20, s21
	s_and_b32 s50, s20, 7
	s_lshr_b32 s21, s20, 5
	s_lshl_b32 s21, s21, 3
	s_add_i32 s50, s50, s21
	s_bfe_u32 s48, s20, 0x20003

.LBB0_1059:
	s_add_i32 s95, s95, 1
	s_mul_i32 s11, s95, s81
	s_mul_hi_u32 s13, s95, s3
	s_add_i32 s13, s13, s11
	s_mul_i32 s11, s95, s3
	v_readlane_b32 s14, v252, 0
	s_add_u32 s14, s11, s14
	s_addc_u32 s15, s13, s80
	v_mov_b64_e32 v[0:1], 0x440
	v_cmp_lt_i64_e64 s[44:45], s[14:15], v[0:1]
	v_mov_b64_e32 v[0:1], 0x43f
	v_cmp_gt_i64_e32 vcc, s[14:15], v[0:1]
	s_cbranch_vccnz .LBB0_1061
	s_and_b32 s11, s14, 7
	s_lshr_b32 s13, s14, 3
	s_mulk_i32 s11, 136
	s_add_i32 s11, s11, s13
	s_and_b32 s12, s11, 7
	s_lshr_b32 s13, s11, 6
	s_lshl_b32 s13, s13, 3
	s_add_i32 s12, s12, s13
	s_bfe_u32 s10, s11, 0x30003
